# h3 item rewritten with all loads issued up front; static prio for waves 0-3 in the attention hot path
# speedup vs baseline: 1.0278x; 1.0065x over previous
.LBB0_622:
	s_or_b64 exec, exec, s[74:75]
	v_lshl_add_u32 v2, s48, 1, v175
	v_lshlrev_b32_e32 v4, 2, v2
	s_movk_i32 s48, 0x7c
	v_and_or_b32 v24, v4, s48, v177
	v_ashrrev_i32_e32 v4, 8, v2
	v_ashrrev_i32_e32 v5, 31, v4
	v_lshlrev_b64 v[4:5], 12, v[4:5]
	v_ashrrev_i32_e32 v20, 5, v2
	v_lshl_or_b32 v2, v24, 5, v4
	v_or_b32_e32 v5, v5, v1
	v_or_b32_e32 v4, v2, v156
	v_lshlrev_b64 v[56:57], 10, v[4:5]
	v_lshlrev_b32_e32 v2, 7, v20
	v_and_b32_e32 v2, 0x380, v2
	v_lshlrev_b64 v[8:9], 1, v[160:161]
	v_mov_b32_e32 v183, v3
	v_lshl_add_u64 v[4:5], s[52:53], 0, v[56:57]
	v_lshl_add_u64 v[4:5], v[4:5], 0, v[2:3]
	v_lshl_add_u64 v[148:149], v[4:5], 0, v[8:9]
	v_lshl_add_u64 v[10:11], s[50:51], 0, v[56:57]
	v_lshl_add_u64 v[10:11], v[10:11], 0, v[2:3]
	v_lshl_add_u64 v[150:151], v[10:11], 0, v[8:9]
	v_lshl_add_u64 v[10:11], s[54:55], 0, v[56:57]
	v_lshl_add_u64 v[10:11], v[10:11], 0, v[2:3]
	v_lshl_add_u64 v[240:241], v[10:11], 0, v[182:183]
	v_lshl_add_u64 v[10:11], s[56:57], 0, v[56:57]
	v_lshl_add_u64 v[10:11], v[10:11], 0, v[2:3]
	v_lshl_add_u64 v[242:243], v[10:11], 0, v[182:183]
	v_ashrrev_i32_e32 v21, 31, v20
	v_lshlrev_b64 v[20:21], 7, v[20:21]
	v_or_b32_e32 v20, v20, v24
	v_lshlrev_b64 v[22:23], 12, v[20:21]
	v_lshl_add_u64 v[152:153], v[180:181], 0, v[22:23]
	v_lshlrev_b64 v[12:13], 13, v[20:21]
	v_lshl_add_u64 v[12:13], v[178:179], 0, v[12:13]
	v_add_co_u32_e32 v154, vcc, 0x1000, v12
	s_nop 1
	v_addc_co_u32_e32 v155, vcc, 0, v13, vcc
	s_mov_b64 s[74:75], 0
	s_mov_b32 s48, 0x800000
	s_barrier
	global_load_dwordx4 v[52:55], v[148:149], off
	global_load_dwordx4 v[68:71], v[150:151], off
	global_load_dwordx4 v[56:59], v[148:149], off offset:32
	global_load_dwordx4 v[72:75], v[150:151], off offset:32
	global_load_dwordx4 v[60:63], v[148:149], off offset:64
	global_load_dwordx4 v[76:79], v[150:151], off offset:64
	global_load_dwordx4 v[64:67], v[148:149], off offset:96
	global_load_dwordx4 v[80:83], v[150:151], off offset:96
	global_load_dwordx4 v[100:103], v[154:155], off offset:-4096
	global_load_dwordx4 v[104:107], v[154:155], off offset:-4064
	global_load_dwordx4 v[108:111], v[154:155], off offset:-4032
	global_load_dwordx4 v[112:115], v[154:155], off offset:-4000
	global_load_dwordx4 v[116:119], v[154:155], off
	global_load_dwordx4 v[120:123], v[154:155], off offset:32
	global_load_dwordx4 v[124:127], v[154:155], off offset:64
	global_load_dwordx4 v[128:131], v[154:155], off offset:96
	global_load_dwordx2 v[84:85], v[152:153], off
	global_load_dwordx2 v[86:87], v[152:153], off offset:16
	global_load_dwordx2 v[88:89], v[152:153], off offset:2048
	global_load_dwordx2 v[90:91], v[152:153], off offset:2064
	global_load_dwordx2 v[92:93], v[152:153], off offset:32
	global_load_dwordx2 v[94:95], v[152:153], off offset:48
	global_load_dwordx2 v[96:97], v[152:153], off offset:2080
	global_load_dwordx2 v[98:99], v[152:153], off offset:2096
	global_load_dwordx2 v[132:133], v[240:241], off
	global_load_dwordx2 v[134:135], v[240:241], off offset:16
	global_load_dwordx2 v[136:137], v[240:241], off offset:32
	global_load_dwordx2 v[138:139], v[240:241], off offset:48
	global_load_dwordx2 v[140:141], v[240:241], off offset:64
	global_load_dwordx2 v[142:143], v[240:241], off offset:80
	global_load_dwordx2 v[144:145], v[240:241], off offset:96
	global_load_dwordx2 v[146:147], v[240:241], off offset:112
	s_waitcnt vmcnt(24)
	v_mfma_f32_32x32x16_bf16 v[36:51], v[52:55], v[68:71], 0
	v_mfma_f32_32x32x16_bf16 v[36:51], v[56:59], v[72:75], v[36:51]
	v_mfma_f32_32x32x16_bf16 v[36:51], v[60:63], v[76:79], v[36:51]
	v_mfma_f32_32x32x16_bf16 v[36:51], v[64:67], v[80:83], v[36:51]
	s_waitcnt vmcnt(16)
	v_mfma_f32_32x32x16_bf16 v[20:35], v[100:103], v[68:71], 0
	v_mfma_f32_32x32x16_bf16 v[4:19], v[116:119], v[68:71], 0
	v_mfma_f32_32x32x16_bf16 v[20:35], v[104:107], v[72:75], v[20:35]
	v_mfma_f32_32x32x16_bf16 v[4:19], v[120:123], v[72:75], v[4:19]
	v_mfma_f32_32x32x16_bf16 v[20:35], v[108:111], v[76:79], v[20:35]
	v_mfma_f32_32x32x16_bf16 v[4:19], v[124:127], v[76:79], v[4:19]
	v_mfma_f32_32x32x16_bf16 v[20:35], v[112:115], v[80:83], v[20:35]
	v_mfma_f32_32x32x16_bf16 v[4:19], v[128:131], v[80:83], v[4:19]
	s_nop 2
	v_cndmask_b32_e64 v44, v44, 0, s[18:19]
	v_cndmask_b32_e64 v45, v45, 0, s[20:21]
	v_cndmask_b32_e64 v46, v46, 0, s[22:23]
	v_cndmask_b32_e64 v47, v47, 0, s[24:25]
	v_cndmask_b32_e64 v48, v48, 0, s[26:27]
	v_cndmask_b32_e64 v49, v49, 0, s[28:29]
	v_cndmask_b32_e64 v50, v50, 0, s[30:31]
	v_cndmask_b32_e64 v51, v51, 0, s[34:35]
	v_cndmask_b32_e64 v240, v36, 0, s[2:3]
	v_cndmask_b32_e64 v241, 0, v37, s[4:5]
	v_cndmask_b32_e64 v38, v38, 0, s[6:7]
	v_cndmask_b32_e64 v39, v39, 0, s[8:9]
	v_cndmask_b32_e64 v40, v40, 0, s[10:11]
	v_cndmask_b32_e64 v41, v41, 0, s[12:13]
	v_cndmask_b32_e64 v42, v42, 0, s[14:15]
	v_cndmask_b32_e64 v43, v43, 0, s[16:17]
	v_cndmask_b32_e64 v240, v240, v36, s[4:5]
	v_cvt_pk_bf16_f32 v36, v240, v241
	v_cvt_pk_bf16_f32 v37, v38, v39
	v_cvt_pk_bf16_f32 v38, v40, v41
	v_cvt_pk_bf16_f32 v39, v42, v43
	v_cvt_pk_bf16_f32 v44, v44, v45
	v_cvt_pk_bf16_f32 v45, v46, v47
	v_cvt_pk_bf16_f32 v46, v48, v49
	v_cvt_pk_bf16_f32 v47, v50, v51
	s_waitcnt vmcnt(8)
	v_mfma_f32_32x32x16_bf16 v[20:35], v[84:87], v[36:39], v[20:35]
	v_mfma_f32_32x32x16_bf16 v[4:19], v[88:91], v[36:39], v[4:19]
	v_mfma_f32_32x32x16_bf16 v[20:35], v[92:95], v[44:47], v[20:35]
	v_mfma_f32_32x32x16_bf16 v[4:19], v[96:99], v[44:47], v[4:19]
	s_waitcnt vmcnt(0)
	v_lshlrev_b32_e32 v52, 16, v132
	v_and_b32_e32 v53, 0xffff0000, v132
	v_lshlrev_b32_e32 v54, 16, v133
	v_and_b32_e32 v55, 0xffff0000, v133
	v_lshlrev_b32_e32 v56, 16, v134
	v_and_b32_e32 v57, 0xffff0000, v134
	v_lshlrev_b32_e32 v58, 16, v135
	v_and_b32_e32 v59, 0xffff0000, v135
	v_lshlrev_b32_e32 v60, 16, v136
	v_and_b32_e32 v61, 0xffff0000, v136
	v_lshlrev_b32_e32 v62, 16, v137
	v_and_b32_e32 v63, 0xffff0000, v137
	v_lshlrev_b32_e32 v64, 16, v138
	v_and_b32_e32 v65, 0xffff0000, v138
	v_lshlrev_b32_e32 v66, 16, v139
	v_and_b32_e32 v67, 0xffff0000, v139
	v_lshlrev_b32_e32 v68, 16, v140
	v_and_b32_e32 v69, 0xffff0000, v140
	v_lshlrev_b32_e32 v70, 16, v141
	v_and_b32_e32 v71, 0xffff0000, v141
	v_lshlrev_b32_e32 v72, 16, v142
	v_and_b32_e32 v73, 0xffff0000, v142
	v_lshlrev_b32_e32 v74, 16, v143
	v_and_b32_e32 v75, 0xffff0000, v143
	v_lshlrev_b32_e32 v76, 16, v144
	v_and_b32_e32 v77, 0xffff0000, v144
	v_lshlrev_b32_e32 v78, 16, v145
	v_and_b32_e32 v79, 0xffff0000, v145
	v_lshlrev_b32_e32 v80, 16, v146
	v_and_b32_e32 v81, 0xffff0000, v146
	v_lshlrev_b32_e32 v82, 16, v147
	v_and_b32_e32 v83, 0xffff0000, v147
	v_mul_f32_e32 v100, v4, v4
	v_mul_f32_e32 v101, v5, v5
	v_mul_f32_e32 v102, v6, v6
	v_mul_f32_e32 v103, v7, v7
	v_mul_f32_e32 v104, v8, v8
	v_mul_f32_e32 v105, v9, v9
	v_mul_f32_e32 v106, v10, v10
	v_mul_f32_e32 v107, v11, v11
	v_mul_f32_e32 v108, v12, v12
	v_mul_f32_e32 v109, v13, v13
	v_mul_f32_e32 v110, v14, v14
	v_mul_f32_e32 v111, v15, v15
	v_mul_f32_e32 v112, v16, v16
	v_mul_f32_e32 v113, v17, v17
	v_mul_f32_e32 v114, v18, v18
	v_mul_f32_e32 v115, v19, v19
	v_fmac_f32_e32 v100, v20, v20
	v_fmac_f32_e32 v101, v21, v21
	v_fmac_f32_e32 v102, v22, v22
	v_fmac_f32_e32 v103, v23, v23
	v_fmac_f32_e32 v104, v24, v24
	v_fmac_f32_e32 v105, v25, v25
	v_fmac_f32_e32 v106, v26, v26
	v_fmac_f32_e32 v107, v27, v27
	v_fmac_f32_e32 v108, v28, v28
	v_fmac_f32_e32 v109, v29, v29
	v_fmac_f32_e32 v110, v30, v30
	v_fmac_f32_e32 v111, v31, v31
	v_fmac_f32_e32 v112, v32, v32
	v_fmac_f32_e32 v113, v33, v33
	v_fmac_f32_e32 v114, v34, v34
	v_fmac_f32_e32 v115, v35, v35
	v_add_f32_e32 v100, v100, v101
	v_add_f32_e32 v100, v100, v102
	v_add_f32_e32 v100, v100, v103
	v_add_f32_e32 v100, v100, v104
	v_add_f32_e32 v100, v100, v105
	v_add_f32_e32 v100, v100, v106
	v_add_f32_e32 v100, v100, v107
	v_add_f32_e32 v100, v100, v108
	v_add_f32_e32 v100, v100, v109
	v_add_f32_e32 v100, v100, v110
	v_add_f32_e32 v100, v100, v111
	v_add_f32_e32 v100, v100, v112
	v_add_f32_e32 v100, v100, v113
	v_add_f32_e32 v100, v100, v114
	v_add_f32_e32 v100, v100, v115
	v_mov_b32_e32 v101, v100
	s_nop 1
	v_permlane32_swap_b32_e32 v100, v101
	v_add_f32_e32 v100, v100, v101
	v_fmamk_f32 v100, v100, 0x3c800000, v159
	v_mul_f32_e32 v101, 0x4b800000, v100
	v_cmp_gt_f32_e32 vcc, s48, v100
	s_nop 1
	v_cndmask_b32_e32 v100, v100, v101, vcc
	v_rsq_f32_e32 v100, v100
	s_nop 0
	v_mul_f32_e32 v101, 0x45800000, v100
	v_cndmask_b32_e32 v100, v100, v101, vcc
	v_mul_f32_e32 v20, v20, v100
	v_mul_f32_e32 v21, v21, v100
	v_mul_f32_e32 v22, v22, v100
	v_mul_f32_e32 v23, v23, v100
	v_mul_f32_e32 v20, v20, v52
	v_mul_f32_e32 v21, v21, v53
	v_mul_f32_e32 v22, v22, v54
	v_mul_f32_e32 v23, v23, v55
	v_cvt_pk_bf16_f32 v20, v20, v21
	v_cvt_pk_bf16_f32 v21, v22, v23
	global_store_dwordx2 v[242:243], v[20:21], off
	v_mul_f32_e32 v24, v24, v100
	v_mul_f32_e32 v25, v25, v100
	v_mul_f32_e32 v26, v26, v100
	v_mul_f32_e32 v27, v27, v100
	v_mul_f32_e32 v24, v24, v56
	v_mul_f32_e32 v25, v25, v57
	v_mul_f32_e32 v26, v26, v58
	v_mul_f32_e32 v27, v27, v59
	v_cvt_pk_bf16_f32 v24, v24, v25
	v_cvt_pk_bf16_f32 v25, v26, v27
	global_store_dwordx2 v[242:243], v[24:25], off offset:16
	v_mul_f32_e32 v28, v28, v100
	v_mul_f32_e32 v29, v29, v100
	v_mul_f32_e32 v30, v30, v100
	v_mul_f32_e32 v31, v31, v100
	v_mul_f32_e32 v28, v28, v60
	v_mul_f32_e32 v29, v29, v61
	v_mul_f32_e32 v30, v30, v62
	v_mul_f32_e32 v31, v31, v63
	v_cvt_pk_bf16_f32 v28, v28, v29
	v_cvt_pk_bf16_f32 v29, v30, v31
	global_store_dwordx2 v[242:243], v[28:29], off offset:32
	v_mul_f32_e32 v32, v32, v100
	v_mul_f32_e32 v33, v33, v100
	v_mul_f32_e32 v34, v34, v100
	v_mul_f32_e32 v35, v35, v100
	v_mul_f32_e32 v32, v32, v64
	v_mul_f32_e32 v33, v33, v65
	v_mul_f32_e32 v34, v34, v66
	v_mul_f32_e32 v35, v35, v67
	v_cvt_pk_bf16_f32 v32, v32, v33
	v_cvt_pk_bf16_f32 v33, v34, v35
	global_store_dwordx2 v[242:243], v[32:33], off offset:48
	v_mul_f32_e32 v4, v4, v100
	v_mul_f32_e32 v5, v5, v100
	v_mul_f32_e32 v6, v6, v100
	v_mul_f32_e32 v7, v7, v100
	v_mul_f32_e32 v4, v4, v68
	v_mul_f32_e32 v5, v5, v69
	v_mul_f32_e32 v6, v6, v70
	v_mul_f32_e32 v7, v7, v71
	v_cvt_pk_bf16_f32 v4, v4, v5
	v_cvt_pk_bf16_f32 v5, v6, v7
	global_store_dwordx2 v[242:243], v[4:5], off offset:64
	v_mul_f32_e32 v8, v8, v100
	v_mul_f32_e32 v9, v9, v100
	v_mul_f32_e32 v10, v10, v100
	v_mul_f32_e32 v11, v11, v100
	v_mul_f32_e32 v8, v8, v72
	v_mul_f32_e32 v9, v9, v73
	v_mul_f32_e32 v10, v10, v74
	v_mul_f32_e32 v11, v11, v75
	v_cvt_pk_bf16_f32 v8, v8, v9
	v_cvt_pk_bf16_f32 v9, v10, v11
	global_store_dwordx2 v[242:243], v[8:9], off offset:80
	v_mul_f32_e32 v12, v12, v100
	v_mul_f32_e32 v13, v13, v100
	v_mul_f32_e32 v14, v14, v100
	v_mul_f32_e32 v15, v15, v100
	v_mul_f32_e32 v12, v12, v76
	v_mul_f32_e32 v13, v13, v77
	v_mul_f32_e32 v14, v14, v78
	v_mul_f32_e32 v15, v15, v79
	v_cvt_pk_bf16_f32 v12, v12, v13
	v_cvt_pk_bf16_f32 v13, v14, v15
	global_store_dwordx2 v[242:243], v[12:13], off offset:96
	v_mul_f32_e32 v16, v16, v100
	v_mul_f32_e32 v17, v17, v100
	v_mul_f32_e32 v18, v18, v100
	v_mul_f32_e32 v19, v19, v100
	v_mul_f32_e32 v16, v16, v80
	v_mul_f32_e32 v17, v17, v81
	v_mul_f32_e32 v18, v18, v82
	v_mul_f32_e32 v19, v19, v83
	v_cvt_pk_bf16_f32 v16, v16, v17
	v_cvt_pk_bf16_f32 v17, v18, v19
	global_store_dwordx2 v[242:243], v[16:17], off offset:112

.LBB0_646:
	s_andn2_saveexec_b64 s[74:75], s[74:75]
	s_cbranch_execz .LBB0_631
	v_mov_b32_e32 v124, v68
	ds_read_b128 v[100:103], v124
	ds_read_b128 v[104:107], v124 offset:32
	ds_read_b128 v[108:111], v124 offset:64
	ds_read_b128 v[112:115], v124 offset:96
	ds_read_b128 v[116:119], v124 offset:128
	ds_read_b128 v[120:123], v124 offset:160
	v_readfirstlane_b32 s76, v0
	s_bitcmp1_b32 s76, 8
	s_cbranch_scc1 .Latt_prio_skip
	s_setprio 1
.Latt_prio_skip:
	v_xor_b32_e32 v84, 0x80000000, v239
	v_mov_b32_e32 v85, v84
	v_mov_b32_e32 v86, v84
	v_mov_b32_e32 v87, v84
	v_mov_b32_e32 v88, v84
	v_mov_b32_e32 v89, v84
	v_mov_b32_e32 v90, v84
	v_mov_b32_e32 v91, v84
	v_mov_b32_e32 v92, v84
	v_mov_b32_e32 v93, v84
	v_mov_b32_e32 v94, v84
	v_mov_b32_e32 v95, v84
	v_mov_b32_e32 v96, v84
	v_mov_b32_e32 v97, v84
	v_mov_b32_e32 v98, v84
	v_mov_b32_e32 v99, v84
	s_waitcnt lgkmcnt(5)
	s_nop 0
	v_mfma_f32_32x32x16_bf16 v[36:51], v[100:103], v[132:135], v[84:99]
	ds_read_b128 v[100:103], v124 offset:6656
	s_waitcnt lgkmcnt(5)
	v_mfma_f32_32x32x16_bf16 v[36:51], v[104:107], v[136:139], v[36:51]
	ds_read_b128 v[104:107], v124 offset:6688
	s_waitcnt lgkmcnt(5)
	v_mfma_f32_32x32x16_bf16 v[36:51], v[108:111], v[140:143], v[36:51]
	ds_read_b128 v[108:111], v124 offset:6720
	s_waitcnt lgkmcnt(5)
	v_mfma_f32_32x32x16_bf16 v[36:51], v[112:115], v[144:147], v[36:51]
	ds_read_b128 v[112:115], v124 offset:6752
	s_waitcnt lgkmcnt(5)
	v_mfma_f32_32x32x16_bf16 v[36:51], v[116:119], v[148:151], v[36:51]
	ds_read_b128 v[116:119], v124 offset:6784
	s_waitcnt lgkmcnt(5)
	v_mfma_f32_32x32x16_bf16 v[36:51], v[120:123], v[152:155], v[36:51]
	ds_read_b128 v[120:123], v124 offset:6816
	s_waitcnt lgkmcnt(5)
	v_mfma_f32_32x32x16_bf16 v[52:67], v[100:103], v[132:135], v[84:99]
	ds_read_b128 v[100:103], v124 offset:13312
	s_waitcnt lgkmcnt(5)
	v_mfma_f32_32x32x16_bf16 v[52:67], v[104:107], v[136:139], v[52:67]
	ds_read_b128 v[104:107], v124 offset:13344
	s_waitcnt lgkmcnt(5)
	v_mfma_f32_32x32x16_bf16 v[52:67], v[108:111], v[140:143], v[52:67]
	ds_read_b128 v[108:111], v124 offset:13376
	s_waitcnt lgkmcnt(5)
	v_mfma_f32_32x32x16_bf16 v[52:67], v[112:115], v[144:147], v[52:67]
	ds_read_b128 v[112:115], v124 offset:13408
	s_waitcnt lgkmcnt(5)
	v_mfma_f32_32x32x16_bf16 v[52:67], v[116:119], v[148:151], v[52:67]
	ds_read_b128 v[116:119], v124 offset:13440
	s_waitcnt lgkmcnt(5)
	v_mfma_f32_32x32x16_bf16 v[52:67], v[120:123], v[152:155], v[52:67]
	ds_read_b128 v[120:123], v124 offset:13472
	s_waitcnt lgkmcnt(5)
	v_mfma_f32_32x32x16_bf16 v[68:83], v[100:103], v[132:135], v[84:99]
	ds_read_b128 v[100:103], v124 offset:19968
	v_max3_f32 v125, v36, v37, v38
	v_max3_f32 v125, v125, v39, v40
	v_max3_f32 v125, v125, v41, v42
	v_max3_f32 v125, v125, v43, v44
	s_waitcnt lgkmcnt(5)
	v_mfma_f32_32x32x16_bf16 v[68:83], v[104:107], v[136:139], v[68:83]
	ds_read_b128 v[104:107], v124 offset:20000
	v_max3_f32 v125, v125, v45, v46
	v_max3_f32 v125, v125, v47, v48
	v_max3_f32 v125, v125, v49, v50
	v_max3_f32 v129, v51, v52, v53
	s_waitcnt lgkmcnt(5)
	v_mfma_f32_32x32x16_bf16 v[68:83], v[108:111], v[140:143], v[68:83]
	ds_read_b128 v[108:111], v124 offset:20032
	v_max3_f32 v129, v129, v54, v55
	v_max3_f32 v129, v129, v56, v57
	v_max3_f32 v129, v129, v58, v59
	v_max3_f32 v129, v129, v60, v61
	s_waitcnt lgkmcnt(5)
	v_mfma_f32_32x32x16_bf16 v[68:83], v[112:115], v[144:147], v[68:83]
	ds_read_b128 v[112:115], v124 offset:20064
	v_max3_f32 v129, v129, v62, v63
	v_max3_f32 v129, v129, v64, v65
	v_max3_f32 v129, v129, v66, v67
	v_max_f32_e32 v125, v125, v129
	s_waitcnt lgkmcnt(5)
	v_mfma_f32_32x32x16_bf16 v[68:83], v[116:119], v[148:151], v[68:83]
	ds_read_b128 v[116:119], v124 offset:20096
	v_mov_b32_e32 v126, v125
	s_nop 1
	v_permlane32_swap_b32_e32 v125, v126
	v_max_f32_e32 v125, v125, v126
	s_cmp_eq_u32 s86, 0
	s_cbranch_scc1 .Latt_slow0
	v_cmp_lt_f32_e32 vcc, s95, v125
	s_cbranch_vccnz .Latt_slow0
	s_waitcnt lgkmcnt(5)
	v_mfma_f32_32x32x16_bf16 v[68:83], v[120:123], v[152:155], v[68:83]
	ds_read_b128 v[120:123], v124 offset:20128
	v_exp_f32_e32 v36, v36
	v_exp_f32_e32 v37, v37
	v_exp_f32_e32 v38, v38
	v_exp_f32_e32 v39, v39
	v_exp_f32_e32 v40, v40
	v_exp_f32_e32 v41, v41
	v_exp_f32_e32 v42, v42
	v_exp_f32_e32 v43, v43
	v_add_f32_e32 v127, v36, v37
	v_add_f32_e32 v127, v38, v127
	v_add_f32_e32 v127, v39, v127
	v_add_f32_e32 v127, v40, v127
	s_waitcnt lgkmcnt(5)
	v_mfma_f32_32x32x16_bf16 v[84:99], v[100:103], v[132:135], v[84:99]
	ds_read_b128 v[100:103], v185 offset:26624
	v_add_f32_e32 v127, v41, v127
	v_add_f32_e32 v127, v42, v127
	v_add_f32_e32 v127, v43, v127
	v_cvt_pk_bf16_f32 v36, v36, v37
	v_cvt_pk_bf16_f32 v37, v38, v39
	v_cvt_pk_bf16_f32 v38, v40, v41
	v_cvt_pk_bf16_f32 v39, v42, v43
	v_exp_f32_e32 v44, v44
	v_exp_f32_e32 v45, v45
	v_exp_f32_e32 v46, v46
	v_exp_f32_e32 v47, v47
	v_exp_f32_e32 v48, v48
	s_waitcnt lgkmcnt(5)
	v_mfma_f32_32x32x16_bf16 v[84:99], v[104:107], v[136:139], v[84:99]
	ds_read_b128 v[104:107], v185 offset:35328
	v_exp_f32_e32 v49, v49
	v_exp_f32_e32 v50, v50
	v_exp_f32_e32 v51, v51
	v_add_f32_e32 v127, v44, v127
	v_add_f32_e32 v127, v45, v127
	v_add_f32_e32 v127, v46, v127
	v_add_f32_e32 v127, v47, v127
	v_add_f32_e32 v127, v48, v127
	v_add_f32_e32 v127, v49, v127
	v_add_f32_e32 v127, v50, v127
	v_add_f32_e32 v127, v51, v127
	v_cvt_pk_bf16_f32 v40, v44, v45
	s_waitcnt lgkmcnt(5)
	v_mfma_f32_32x32x16_bf16 v[84:99], v[108:111], v[140:143], v[84:99]
	ds_read_b128 v[108:111], v185 offset:26656
	v_cvt_pk_bf16_f32 v41, v46, v47
	v_cvt_pk_bf16_f32 v42, v48, v49
	v_cvt_pk_bf16_f32 v43, v50, v51
	v_exp_f32_e32 v52, v52
	v_exp_f32_e32 v53, v53
	v_exp_f32_e32 v54, v54
	v_exp_f32_e32 v55, v55
	v_exp_f32_e32 v56, v56
	v_exp_f32_e32 v57, v57
	v_exp_f32_e32 v58, v58
	v_exp_f32_e32 v59, v59
	v_add_f32_e32 v128, v52, v53
	s_waitcnt lgkmcnt(5)
	v_mfma_f32_32x32x16_bf16 v[84:99], v[112:115], v[144:147], v[84:99]
	ds_read_b128 v[112:115], v185 offset:35360
	v_add_f32_e32 v128, v54, v128
	v_add_f32_e32 v128, v55, v128
	v_add_f32_e32 v128, v56, v128
	v_add_f32_e32 v128, v57, v128
	v_add_f32_e32 v128, v58, v128
	v_add_f32_e32 v128, v59, v128
	v_cvt_pk_bf16_f32 v52, v52, v53
	v_cvt_pk_bf16_f32 v53, v54, v55
	v_cvt_pk_bf16_f32 v54, v56, v57
	v_cvt_pk_bf16_f32 v55, v58, v59
	v_exp_f32_e32 v60, v60
	v_exp_f32_e32 v61, v61
	s_waitcnt lgkmcnt(5)
	v_mfma_f32_32x32x16_bf16 v[84:99], v[116:119], v[148:151], v[84:99]
	ds_read_b128 v[116:119], v185 offset:26688
	v_exp_f32_e32 v62, v62
	v_exp_f32_e32 v63, v63
	v_exp_f32_e32 v64, v64
	v_exp_f32_e32 v65, v65
	v_exp_f32_e32 v66, v66
	v_exp_f32_e32 v67, v67
	v_add_f32_e32 v128, v60, v128
	v_add_f32_e32 v128, v61, v128
	v_add_f32_e32 v128, v62, v128
	v_add_f32_e32 v128, v63, v128
	v_add_f32_e32 v128, v64, v128
	v_add_f32_e32 v128, v65, v128
	s_waitcnt lgkmcnt(5)
	v_mfma_f32_32x32x16_bf16 v[84:99], v[120:123], v[152:155], v[84:99]
	ds_read_b128 v[120:123], v185 offset:35392
	v_add_f32_e32 v128, v66, v128
	v_add_f32_e32 v128, v67, v128
	v_cvt_pk_bf16_f32 v56, v60, v61
	v_cvt_pk_bf16_f32 v57, v62, v63
	v_cvt_pk_bf16_f32 v58, v64, v65
	v_cvt_pk_bf16_f32 v59, v66, v67
	v_add_f32_e32 v127, v127, v128
	v_add_f32_e32 v238, v238, v127
	s_waitcnt lgkmcnt(5)
	v_mfma_f32_32x32x16_bf16 v[4:19], v[100:103], v[36:39], v[4:19]
	ds_read_b128 v[100:103], v185 offset:26720
	v_max3_f32 v125, v68, v69, v70
	v_max3_f32 v125, v125, v71, v72
	v_max3_f32 v125, v125, v73, v74
	v_max3_f32 v125, v125, v75, v76
	v_max3_f32 v125, v125, v77, v78
	v_max3_f32 v125, v125, v79, v80
	v_max3_f32 v125, v125, v81, v82
	s_waitcnt lgkmcnt(5)
	v_mfma_f32_32x32x16_bf16 v[20:35], v[104:107], v[36:39], v[20:35]
	ds_read_b128 v[104:107], v185 offset:35424
	v_max3_f32 v129, v83, v84, v85
	v_max3_f32 v129, v129, v86, v87
	v_max3_f32 v129, v129, v88, v89
	v_max3_f32 v129, v129, v90, v91
	v_max3_f32 v129, v129, v92, v93
	v_max3_f32 v129, v129, v94, v95
	v_max3_f32 v129, v129, v96, v97
	s_waitcnt lgkmcnt(5)
	v_mfma_f32_32x32x16_bf16 v[4:19], v[108:111], v[40:43], v[4:19]
	ds_read_b128 v[108:111], v185 offset:26752
	v_max3_f32 v129, v129, v98, v99
	v_max_f32_e32 v125, v125, v129
	v_mov_b32_e32 v126, v125
	s_nop 1
	v_permlane32_swap_b32_e32 v125, v126
	v_max_f32_e32 v125, v125, v126
	v_cmp_lt_f32_e32 vcc, s95, v125
	s_cbranch_vccnz .Latt_slow1
	s_waitcnt lgkmcnt(5)
	v_mfma_f32_32x32x16_bf16 v[20:35], v[112:115], v[40:43], v[20:35]
	ds_read_b128 v[112:115], v185 offset:35456
	v_exp_f32_e32 v68, v68
	v_exp_f32_e32 v69, v69
	v_exp_f32_e32 v70, v70
	v_exp_f32_e32 v71, v71
	v_exp_f32_e32 v72, v72
	v_exp_f32_e32 v73, v73
	v_exp_f32_e32 v74, v74
	v_exp_f32_e32 v75, v75
	v_add_f32_e32 v127, v68, v69
	v_add_f32_e32 v127, v70, v127
	v_add_f32_e32 v127, v71, v127
	v_add_f32_e32 v127, v72, v127
	v_add_f32_e32 v127, v73, v127
	v_add_f32_e32 v127, v74, v127
	v_add_f32_e32 v127, v75, v127
	v_cvt_pk_bf16_f32 v68, v68, v69
	s_waitcnt lgkmcnt(5)
	v_mfma_f32_32x32x16_bf16 v[4:19], v[116:119], v[52:55], v[4:19]
	ds_read_b128 v[116:119], v185 offset:26784
	v_cvt_pk_bf16_f32 v69, v70, v71
	v_cvt_pk_bf16_f32 v70, v72, v73
	v_cvt_pk_bf16_f32 v71, v74, v75
	v_exp_f32_e32 v76, v76
	v_exp_f32_e32 v77, v77
	v_exp_f32_e32 v78, v78
	v_exp_f32_e32 v79, v79
	v_exp_f32_e32 v80, v80
	v_exp_f32_e32 v81, v81
	v_exp_f32_e32 v82, v82
	v_exp_f32_e32 v83, v83
	v_add_f32_e32 v127, v76, v127
	v_add_f32_e32 v127, v77, v127
	v_add_f32_e32 v127, v78, v127
	v_add_f32_e32 v127, v79, v127
	v_add_f32_e32 v127, v80, v127
	s_waitcnt lgkmcnt(5)
	v_mfma_f32_32x32x16_bf16 v[20:35], v[120:123], v[52:55], v[20:35]
	ds_read_b128 v[120:123], v185 offset:35488
	v_add_f32_e32 v127, v81, v127
	v_add_f32_e32 v127, v82, v127
	v_add_f32_e32 v127, v83, v127
	v_cvt_pk_bf16_f32 v72, v76, v77
	v_cvt_pk_bf16_f32 v73, v78, v79
	v_cvt_pk_bf16_f32 v74, v80, v81
	v_cvt_pk_bf16_f32 v75, v82, v83
	v_exp_f32_e32 v84, v84
	v_exp_f32_e32 v85, v85
	v_exp_f32_e32 v86, v86
	v_exp_f32_e32 v87, v87
	v_exp_f32_e32 v88, v88
	v_exp_f32_e32 v89, v89
	v_exp_f32_e32 v90, v90
	v_exp_f32_e32 v91, v91
	v_add_f32_e32 v128, v84, v85
	s_waitcnt lgkmcnt(5)
	v_mfma_f32_32x32x16_bf16 v[4:19], v[100:103], v[56:59], v[4:19]
	ds_read_b128 v[100:103], v185 offset:26816
	v_add_f32_e32 v128, v86, v128
	v_add_f32_e32 v128, v87, v128
	v_add_f32_e32 v128, v88, v128
	v_add_f32_e32 v128, v89, v128
	v_add_f32_e32 v128, v90, v128
	v_add_f32_e32 v128, v91, v128
	v_cvt_pk_bf16_f32 v84, v84, v85
	v_cvt_pk_bf16_f32 v85, v86, v87
	v_cvt_pk_bf16_f32 v86, v88, v89
	v_cvt_pk_bf16_f32 v87, v90, v91
	v_exp_f32_e32 v92, v92
	v_exp_f32_e32 v93, v93
	v_exp_f32_e32 v94, v94
	v_exp_f32_e32 v95, v95
	v_exp_f32_e32 v96, v96
	v_exp_f32_e32 v97, v97
	s_waitcnt lgkmcnt(5)
	v_mfma_f32_32x32x16_bf16 v[20:35], v[104:107], v[56:59], v[20:35]
	ds_read_b128 v[104:107], v185 offset:35520
	v_exp_f32_e32 v98, v98
	v_exp_f32_e32 v99, v99
	v_add_f32_e32 v128, v92, v128
	v_add_f32_e32 v128, v93, v128
	v_add_f32_e32 v128, v94, v128
	v_add_f32_e32 v128, v95, v128
	v_add_f32_e32 v128, v96, v128
	v_add_f32_e32 v128, v97, v128
	v_add_f32_e32 v128, v98, v128
	v_add_f32_e32 v128, v99, v128
	v_cvt_pk_bf16_f32 v88, v92, v93
	v_cvt_pk_bf16_f32 v89, v94, v95
	v_cvt_pk_bf16_f32 v90, v96, v97
	v_cvt_pk_bf16_f32 v91, v98, v99
	v_add_f32_e32 v127, v127, v128
	v_add_f32_e32 v238, v238, v127
	s_waitcnt lgkmcnt(5)
	v_mfma_f32_32x32x16_bf16 v[4:19], v[108:111], v[68:71], v[4:19]
	ds_read_b128 v[108:111], v185 offset:26848
	s_waitcnt lgkmcnt(5)
	v_mfma_f32_32x32x16_bf16 v[20:35], v[112:115], v[68:71], v[20:35]
	ds_read_b128 v[112:115], v185 offset:35552
	s_waitcnt lgkmcnt(5)
	v_mfma_f32_32x32x16_bf16 v[4:19], v[116:119], v[72:75], v[4:19]
	s_waitcnt lgkmcnt(4)
	v_mfma_f32_32x32x16_bf16 v[20:35], v[120:123], v[72:75], v[20:35]
	s_waitcnt lgkmcnt(3)
	v_mfma_f32_32x32x16_bf16 v[4:19], v[100:103], v[84:87], v[4:19]
	s_waitcnt lgkmcnt(2)
	v_mfma_f32_32x32x16_bf16 v[20:35], v[104:107], v[84:87], v[20:35]
	s_waitcnt lgkmcnt(1)
	v_mfma_f32_32x32x16_bf16 v[4:19], v[108:111], v[88:91], v[4:19]
	s_waitcnt lgkmcnt(0)
	v_mfma_f32_32x32x16_bf16 v[20:35], v[112:115], v[88:91], v[20:35]
	s_setprio 0
	s_branch .LBB0_631

.Latt_slowb:
	s_waitcnt lgkmcnt(5)
	v_mfma_f32_32x32x16_bf16 v[20:35], v[112:115], v[40:43], v[20:35]
	ds_read_b128 v[112:115], v185 offset:35456
	s_waitcnt lgkmcnt(5)
	v_mfma_f32_32x32x16_bf16 v[4:19], v[116:119], v[52:55], v[4:19]
	ds_read_b128 v[116:119], v185 offset:26784
	s_waitcnt lgkmcnt(5)
	v_mfma_f32_32x32x16_bf16 v[20:35], v[120:123], v[52:55], v[20:35]
	ds_read_b128 v[120:123], v185 offset:35488
	s_waitcnt lgkmcnt(5)
	v_mfma_f32_32x32x16_bf16 v[4:19], v[100:103], v[56:59], v[4:19]
	ds_read_b128 v[100:103], v185 offset:26816
	s_waitcnt lgkmcnt(5)
	v_mfma_f32_32x32x16_bf16 v[20:35], v[104:107], v[56:59], v[20:35]
	ds_read_b128 v[104:107], v185 offset:35520
	v_max3_f32 v125, v68, v69, v70
	v_max3_f32 v125, v125, v71, v72
	v_max3_f32 v125, v125, v73, v74
	v_max3_f32 v125, v125, v75, v76
	v_max3_f32 v125, v125, v77, v78
	v_max3_f32 v125, v125, v79, v80
	v_max3_f32 v125, v125, v81, v82
	v_max3_f32 v129, v83, v84, v85
	v_max3_f32 v129, v129, v86, v87
	v_max3_f32 v129, v129, v88, v89
	v_max3_f32 v129, v129, v90, v91
	v_max3_f32 v129, v129, v92, v93
	v_max3_f32 v129, v129, v94, v95
	v_max3_f32 v129, v129, v96, v97
	v_max3_f32 v129, v129, v98, v99
	v_max_f32_e32 v125, v125, v129
	v_mov_b32_e32 v126, v125
	s_nop 1
	v_permlane32_swap_b32_e32 v125, v126
	v_max_f32_e32 v125, v125, v126
	v_sub_f32_e32 v125, v125, v242
	v_max_f32_e32 v130, 0, v125
	v_exp_f32_e64 v131, -v130
	v_add_f32_e32 v187, v242, v130
	v_add_f32_e32 v239, v239, v130
	v_sub_f32_e32 v68, v68, v187
	v_sub_f32_e32 v69, v69, v187
	v_sub_f32_e32 v70, v70, v187
	v_sub_f32_e32 v71, v71, v187
	v_sub_f32_e32 v72, v72, v187
	v_sub_f32_e32 v73, v73, v187
	v_sub_f32_e32 v74, v74, v187
	v_sub_f32_e32 v75, v75, v187
	v_sub_f32_e32 v76, v76, v187
	v_sub_f32_e32 v77, v77, v187
	v_sub_f32_e32 v78, v78, v187
	v_sub_f32_e32 v79, v79, v187
	v_sub_f32_e32 v80, v80, v187
	v_sub_f32_e32 v81, v81, v187
	v_sub_f32_e32 v82, v82, v187
	v_sub_f32_e32 v83, v83, v187
	v_sub_f32_e32 v84, v84, v187
	v_sub_f32_e32 v85, v85, v187
	v_sub_f32_e32 v86, v86, v187
	v_sub_f32_e32 v87, v87, v187
	v_sub_f32_e32 v88, v88, v187
	v_sub_f32_e32 v89, v89, v187
	v_sub_f32_e32 v90, v90, v187
	v_sub_f32_e32 v91, v91, v187
	v_sub_f32_e32 v92, v92, v187
	v_sub_f32_e32 v93, v93, v187
	v_sub_f32_e32 v94, v94, v187
	v_sub_f32_e32 v95, v95, v187
	v_sub_f32_e32 v96, v96, v187
	v_sub_f32_e32 v97, v97, v187
	v_sub_f32_e32 v98, v98, v187
	v_sub_f32_e32 v99, v99, v187
	v_exp_f32_e32 v68, v68
	v_exp_f32_e32 v69, v69
	v_exp_f32_e32 v70, v70
	v_exp_f32_e32 v71, v71
	v_exp_f32_e32 v72, v72
	v_exp_f32_e32 v73, v73
	v_exp_f32_e32 v74, v74
	v_exp_f32_e32 v75, v75
	v_exp_f32_e32 v76, v76
	v_exp_f32_e32 v77, v77
	v_exp_f32_e32 v78, v78
	v_exp_f32_e32 v79, v79
	v_exp_f32_e32 v80, v80
	v_exp_f32_e32 v81, v81
	v_exp_f32_e32 v82, v82
	v_exp_f32_e32 v83, v83
	v_exp_f32_e32 v84, v84
	v_exp_f32_e32 v85, v85
	v_exp_f32_e32 v86, v86
	v_exp_f32_e32 v87, v87
	v_exp_f32_e32 v88, v88
	v_exp_f32_e32 v89, v89
	v_exp_f32_e32 v90, v90
	v_exp_f32_e32 v91, v91
	v_exp_f32_e32 v92, v92
	v_exp_f32_e32 v93, v93
	v_exp_f32_e32 v94, v94
	v_exp_f32_e32 v95, v95
	v_exp_f32_e32 v96, v96
	v_exp_f32_e32 v97, v97
	v_exp_f32_e32 v98, v98
	v_exp_f32_e32 v99, v99
	v_add_f32_e32 v127, v68, v69
	v_add_f32_e32 v127, v70, v127
	v_add_f32_e32 v127, v71, v127
	v_add_f32_e32 v127, v72, v127
	v_add_f32_e32 v127, v73, v127
	v_add_f32_e32 v127, v74, v127
	v_add_f32_e32 v127, v75, v127
	v_add_f32_e32 v127, v76, v127
	v_add_f32_e32 v127, v77, v127
	v_add_f32_e32 v127, v78, v127
	v_add_f32_e32 v127, v79, v127
	v_add_f32_e32 v127, v80, v127
	v_add_f32_e32 v127, v81, v127
	v_add_f32_e32 v127, v82, v127
	v_add_f32_e32 v127, v83, v127
	v_add_f32_e32 v127, v84, v127
	v_add_f32_e32 v127, v85, v127
	v_add_f32_e32 v127, v86, v127
	v_add_f32_e32 v127, v87, v127
	v_add_f32_e32 v127, v88, v127
	v_add_f32_e32 v127, v89, v127
	v_add_f32_e32 v127, v90, v127
	v_add_f32_e32 v127, v91, v127
	v_add_f32_e32 v127, v92, v127
	v_add_f32_e32 v127, v93, v127
	v_add_f32_e32 v127, v94, v127
	v_add_f32_e32 v127, v95, v127
	v_add_f32_e32 v127, v96, v127
	v_add_f32_e32 v127, v97, v127
	v_add_f32_e32 v127, v98, v127
	v_add_f32_e32 v127, v99, v127
	v_mul_f32_e32 v238, v238, v131
	v_add_f32_e32 v238, v238, v127
	v_mul_f32_e32 v4, v4, v131
	v_mul_f32_e32 v5, v5, v131
	v_mul_f32_e32 v6, v6, v131
	v_mul_f32_e32 v7, v7, v131
	v_mul_f32_e32 v8, v8, v131
	v_mul_f32_e32 v9, v9, v131
	v_mul_f32_e32 v10, v10, v131
	v_mul_f32_e32 v11, v11, v131
	v_mul_f32_e32 v12, v12, v131
	v_mul_f32_e32 v13, v13, v131
	v_mul_f32_e32 v14, v14, v131
	v_mul_f32_e32 v15, v15, v131
	v_mul_f32_e32 v16, v16, v131
	v_mul_f32_e32 v17, v17, v131
	v_mul_f32_e32 v18, v18, v131
	v_mul_f32_e32 v19, v19, v131
	v_mul_f32_e32 v20, v20, v131
	v_mul_f32_e32 v21, v21, v131
	v_mul_f32_e32 v22, v22, v131
	v_mul_f32_e32 v23, v23, v131
	v_mul_f32_e32 v24, v24, v131
	v_mul_f32_e32 v25, v25, v131
	v_mul_f32_e32 v26, v26, v131
	v_mul_f32_e32 v27, v27, v131
	v_mul_f32_e32 v28, v28, v131
	v_mul_f32_e32 v29, v29, v131
	v_mul_f32_e32 v30, v30, v131
	v_mul_f32_e32 v31, v31, v131
	v_mul_f32_e32 v32, v32, v131
	v_mul_f32_e32 v33, v33, v131
	v_mul_f32_e32 v34, v34, v131
	v_mul_f32_e32 v35, v35, v131
	v_mov_b32_e32 v242, v130
	v_cvt_pk_bf16_f32 v68, v68, v69
	v_cvt_pk_bf16_f32 v69, v70, v71
	v_cvt_pk_bf16_f32 v70, v72, v73
	v_cvt_pk_bf16_f32 v71, v74, v75
	v_cvt_pk_bf16_f32 v72, v76, v77
	v_cvt_pk_bf16_f32 v73, v78, v79
	v_cvt_pk_bf16_f32 v74, v80, v81
	v_cvt_pk_bf16_f32 v75, v82, v83
	v_cvt_pk_bf16_f32 v84, v84, v85
	v_cvt_pk_bf16_f32 v85, v86, v87
	v_cvt_pk_bf16_f32 v86, v88, v89
	v_cvt_pk_bf16_f32 v87, v90, v91
	v_cvt_pk_bf16_f32 v88, v92, v93
	v_cvt_pk_bf16_f32 v89, v94, v95
	v_cvt_pk_bf16_f32 v90, v96, v97
	v_cvt_pk_bf16_f32 v91, v98, v99
	s_waitcnt lgkmcnt(5)
	v_mfma_f32_32x32x16_bf16 v[4:19], v[108:111], v[68:71], v[4:19]
	ds_read_b128 v[108:111], v185 offset:26848
	s_waitcnt lgkmcnt(5)
	v_mfma_f32_32x32x16_bf16 v[20:35], v[112:115], v[68:71], v[20:35]
	ds_read_b128 v[112:115], v185 offset:35552
	s_waitcnt lgkmcnt(5)
	v_mfma_f32_32x32x16_bf16 v[4:19], v[116:119], v[72:75], v[4:19]
	s_waitcnt lgkmcnt(4)
	v_mfma_f32_32x32x16_bf16 v[20:35], v[120:123], v[72:75], v[20:35]
	s_waitcnt lgkmcnt(3)
	v_mfma_f32_32x32x16_bf16 v[4:19], v[100:103], v[84:87], v[4:19]
	s_waitcnt lgkmcnt(2)
	v_mfma_f32_32x32x16_bf16 v[20:35], v[104:107], v[84:87], v[20:35]
	s_waitcnt lgkmcnt(1)
	v_mfma_f32_32x32x16_bf16 v[4:19], v[108:111], v[88:91], v[4:19]
	s_waitcnt lgkmcnt(0)
	v_mfma_f32_32x32x16_bf16 v[20:35], v[112:115], v[88:91], v[20:35]
	s_setprio 0
	s_branch .LBB0_631
